# v38 with the whole instruction stream shifted by 28 bytes (7 s_nop at entry): code placement trial
# speedup vs baseline: 1.0032x; 1.0001x over previous
; #define LAS __attribute__((address_space(3)))
; __global__ void __launch_bounds__(512, 2) fwd_mega(Args args) {
;     extern __shared__ __attribute__((aligned(16))) unsigned char lds_raw[];
;     LAS unsigned char* lds = (LAS unsigned char*)lds_raw;
;     cg::grid_group grid = cg::this_grid();
;     const int tid = threadIdx.x, lane = tid & 63, wave = __builtin_amdgcn_readfirstlane(tid >> 6);
;     const int G = gridDim.x, bx = blockIdx.x;
;     const float* x = args.in[0]; const float* mem = args.in[1]; const int* positions = (const int*)args.in[2];
;     float* out = args.out;
;     const int lo = args.ph_lo, hi = args.ph_hi;
;     ...
;     if (args.ph_lo < 0) grid.sync();
_Z8fwd_mega4Args:
	s_nop 0
	s_nop 0
	s_nop 0
	s_nop 0
	s_nop 0
	s_nop 0
	s_nop 0
	s_mov_b32 s96, s2
	s_load_dwordx4 s[84:87], s[0:1], 0x100
	s_load_dword s2, s[0:1], 0x110
	s_add_u32 s4, s0, 0x108
	s_addc_u32 s5, s1, 0
	v_and_b32_e32 v196, 0x3ff, v0
	s_waitcnt lgkmcnt(0)
	s_cmp_gt_i32 s84, -1
	v_writelane_b32 v249, s2, 0
	s_movk_i32 s2, 0x3ff
	v_readfirstlane_b32 s10, v196
	s_cbranch_scc1 .LBB0_12
	v_lshrrev_b32_e32 v1, 20, v0
	v_lshrrev_b32_e32 v0, 10, v0
	v_or_b32_e32 v0, v0, v1
	v_and_or_b32 v0, v0, s2, v196
	v_cmp_eq_u32_e32 vcc, 0, v0
	s_barrier
	s_and_saveexec_b64 s[2:3], vcc
	s_cbranch_execz .LBB0_11
	buffer_wbl2 sc1
	s_load_dwordx2 s[4:5], s[4:5], 0x58
	s_mov_b64 s[6:7], exec
	v_mbcnt_lo_u32_b32 v0, s6, 0
	v_mbcnt_hi_u32_b32 v0, s7, v0
	v_cmp_eq_u32_e32 vcc, 0, v0
	s_waitcnt lgkmcnt(0)
	s_load_dword s11, s[4:5], 0x28
	s_and_saveexec_b64 s[8:9], vcc
	s_cbranch_execz .LBB0_4
	s_bcnt1_i32_b64 s6, s[6:7]
	v_mov_b32_e32 v1, 0
	v_mov_b32_e32 v2, s6
	global_atomic_add v1, v1, v2, s[4:5] offset:32 sc0
